# FIN loop rolling prefetch: each sub-iteration slot reloads for the next trip right after its store, so load latency hides behind the other four slots' math
# speedup vs baseline: 1.0007x; 1.0007x over previous
; DI float bflo(unsigned v) { return __uint_as_float(v << 16); }
; DI float bfhi(unsigned v) { return __uint_as_float(v & 0xffff0000u); }
; DI int opaque_tid(const VBC& vc) { int t = ((vc.wid & 3) << 6) | lane_id(); asm volatile("" : "+v"(t)); return t; }
; DI void phase_fin(const Params& p, int layer, const VBC& vc) {
;     const int ntok = layer < DEPTH - 1 ? NTOK : NLAT;
;     const u16* P = (const u16*)(p.ws + OFF_P);
;     const u16* HF = (const u16*)(p.ws + OFF_HD); const u16* HB = HF + (size_t)NTOK * 384;
;     u16* Y = (u16*)(p.ws + OFF_HY);
;     const float* gn = p.mng + layer * 384;
;     const int tid = opaque_tid(vc);
;     for (long idx = (long)VBID * 256 + tid; idx < (long)ntok * 96; idx += (long)VGRID * 256) {
;         const int tok = (int)(idx / 96), rem = (int)(idx % 96), hd = rem >> 4, q = rem & 15, col = hd * 64 + q * 4;
;         uint2 a = *(const uint2*)(HF + (size_t)tok * 384 + col), bq = *(const uint2*)(HB + (size_t)tok * 384 + col);
;         float s0 = bflo(a.x) + bflo(bq.x), s1 = bfhi(a.x) + bfhi(bq.x), s2 = bflo(a.y) + bflo(bq.y), s3 = bfhi(a.y) + bfhi(bq.y);
;         float ss = s0 * s0 + s1 * s1 + s2 * s2 + s3 * s3;
;         ss += __shfl_xor(ss, 1); ss += __shfl_xor(ss, 2); ss += __shfl_xor(ss, 4); ss += __shfl_xor(ss, 8);
;         const float rs = rsqrtf(ss * (1.f / 64.f) + LN_EPS);
;         float4 gv = *(const float4*)(gn + col);
;         uint2 o = *(const uint2*)(P + (size_t)tok * PC + P_OM + col), z = *(const uint2*)(P + (size_t)tok * PC + P_ZM + col);
.LBB0_1120:
	s_andn2_b64 vcc, exec, s[0:1]
	s_cbranch_vccnz .LBB0_1180
	v_readlane_b32 s0, v251, 60
	v_readlane_b32 s1, v251, 61
	s_cmp_eq_u32 s0, 3
	v_readlane_b32 s0, v252, 21
	v_mbcnt_lo_u32_b32 v0, -1, 0
	v_mbcnt_hi_u32_b32 v0, -1, v0
	s_nop 1
	v_or_b32_e32 v2, s0, v0
	v_readlane_b32 s0, v252, 22
	v_readlane_b32 s1, v252, 23
	v_ashrrev_i32_e32 v3, 31, v2
	s_nop 0
	v_lshl_add_u64 v[2:3], s[0:1], 0, v[2:3]
	s_mov_b32 s0, 0x300000
	s_cselect_b32 s0, s0, 0x330000
	s_mov_b32 s1, s53
	v_cmp_gt_i64_e32 vcc, s[0:1], v[2:3]
	s_and_saveexec_b64 s[2:3], vcc
	s_waitcnt lgkmcnt(0)
	s_movk_i32 s24, 0x300
	s_mov_b32 s25, 0x800000
	s_waitcnt lgkmcnt(0)
	s_mov_b32 s26, 0xaaaaaaab
	s_mov_b32 s27, 0x2aaaaaaa
	s_cbranch_execz .LBB0_1124
	v_and_b32_e32 v4, 64, v237
	v_xor_b32_e32 v0, 1, v237
	v_add_u32_e32 v4, 64, v4
	v_cmp_lt_i32_e32 vcc, v0, v4
	v_readlane_b32 s6, v252, 40
	v_readlane_b32 s7, v252, 41
	v_cndmask_b32_e32 v0, v237, v0, vcc
	v_lshlrev_b32_e32 v5, 2, v0
	v_xor_b32_e32 v0, 2, v237
	v_readlane_b32 s4, v251, 60
	v_readlane_b32 s8, v252, 3
	v_cmp_lt_i32_e32 vcc, v0, v4
	s_load_dword s6, s[6:7], 0x0
	v_readlane_b32 s5, v251, 61
	v_readlane_b32 s9, v252, 4
	v_readlane_b32 s10, v252, 5
	v_readlane_b32 s11, v252, 6
	v_readlane_b32 s12, v252, 7
	v_readlane_b32 s13, v252, 8
	v_cndmask_b32_e32 v0, v237, v0, vcc
	s_mulk_i32 s4, 0x180
	s_mov_b32 s5, s53
	v_readlane_b32 s14, v252, 9
	v_readlane_b32 s15, v252, 10
	v_readlane_b32 s16, v252, 11
	v_readlane_b32 s17, v252, 12
	s_mov_b64 s[8:9], s[12:13]
	v_lshlrev_b32_e32 v6, 2, v0
	v_xor_b32_e32 v0, 4, v237
	s_lshl_b64 s[4:5], s[4:5], 2
	s_mov_b64 s[10:11], s[14:15]
	s_mov_b64 s[12:13], s[16:17]
	v_cmp_lt_i32_e32 vcc, v0, v4
	s_add_u32 s4, s12, s4
	s_addc_u32 s5, s13, s5
	v_cndmask_b32_e32 v0, v237, v0, vcc
	v_lshlrev_b32_e32 v7, 2, v0
	v_xor_b32_e32 v0, 8, v237
	s_waitcnt lgkmcnt(0)
	s_lshl_b32 s6, s6, 1
	v_cmp_lt_i32_e32 vcc, v0, v4
	s_ashr_i32 s7, s6, 31
	v_readlane_b32 s16, v251, 33
	v_readlane_b32 s14, v251, 12
	v_cndmask_b32_e32 v0, v237, v0, vcc
	s_lshl_b64 s[6:7], s[6:7], 8
	v_readlane_b32 s17, v251, 34
	v_readlane_b32 s15, v251, 13
	v_lshlrev_b32_e32 v8, 2, v0
	v_lshlrev_b32_e32 v4, 2, v2
	s_lshl_b32 s10, s6, 2
	s_mov_b64 s[8:9], 0
	v_readlane_b32 s18, v252, 13
	v_readlane_b32 s19, v252, 14
	v_readlane_b32 s20, v252, 15
	v_readlane_b32 s21, v252, 16
	v_readlane_b32 s22, v252, 17
	v_readlane_b32 s23, v252, 18
	s_add_i32 s11, s0, -1
	s_mul_i32 s9, s6, 5
	v_mov_b32_e32 v73, v2
	v_min_u32_e32 v20, s11, v73
	v_mul_hi_u32 v21, v20, s26
	v_lshrrev_b32_e32 v21, 6, v21
	v_mul_u32_u24_e32 v22, 0x60, v21
	v_sub_u32_e32 v22, v20, v22
	v_lshlrev_b32_e32 v23, 3, v22
	v_mul_u32_u24_e32 v24, 0x300, v21
	v_add_u32_e32 v24, v24, v23
	v_mul_lo_u32 v25, v21, s67
	v_add3_u32 v25, v25, v23, s61
	v_lshlrev_b32_e32 v26, 4, v22
	v_lshlrev_b32_e32 v27, 11, v21
	v_add_u32_e32 v27, 0x2a6f000, v27
	v_add_u32_e32 v72, v27, v23
	global_load_dwordx2 v[60:61], v24, s[14:15]
	global_load_dwordx2 v[62:63], v24, s[16:17]
	global_load_dwordx2 v[64:65], v25, s[36:37] offset:1024
	global_load_dwordx2 v[66:67], v25, s[36:37] offset:1792
	global_load_dwordx4 v[68:71], v26, s[4:5]
	v_add_u32_e32 v89, s6, v2
	v_min_u32_e32 v20, s11, v89
	v_mul_hi_u32 v21, v20, s26
	v_lshrrev_b32_e32 v21, 6, v21
	v_mul_u32_u24_e32 v22, 0x60, v21
	v_sub_u32_e32 v22, v20, v22
	v_lshlrev_b32_e32 v23, 3, v22
	v_mul_u32_u24_e32 v24, 0x300, v21
	v_add_u32_e32 v24, v24, v23
	v_mul_lo_u32 v25, v21, s67
	v_add3_u32 v25, v25, v23, s61
	v_lshlrev_b32_e32 v26, 4, v22
	v_lshlrev_b32_e32 v27, 11, v21
	v_add_u32_e32 v27, 0x2a6f000, v27
	v_add_u32_e32 v88, v27, v23
	global_load_dwordx2 v[76:77], v24, s[14:15]
	global_load_dwordx2 v[78:79], v24, s[16:17]
	global_load_dwordx2 v[80:81], v25, s[36:37] offset:1024
	global_load_dwordx2 v[82:83], v25, s[36:37] offset:1792
	global_load_dwordx4 v[84:87], v26, s[4:5]
	s_mul_i32 s8, s6, 2
	v_add_u32_e32 v105, s8, v2
	v_min_u32_e32 v20, s11, v105
	v_mul_hi_u32 v21, v20, s26
	v_lshrrev_b32_e32 v21, 6, v21
	v_mul_u32_u24_e32 v22, 0x60, v21
	v_sub_u32_e32 v22, v20, v22
	v_lshlrev_b32_e32 v23, 3, v22
	v_mul_u32_u24_e32 v24, 0x300, v21
	v_add_u32_e32 v24, v24, v23
	v_mul_lo_u32 v25, v21, s67
	v_add3_u32 v25, v25, v23, s61
	v_lshlrev_b32_e32 v26, 4, v22
	v_lshlrev_b32_e32 v27, 11, v21
	v_add_u32_e32 v27, 0x2a6f000, v27
	v_add_u32_e32 v104, v27, v23
	global_load_dwordx2 v[92:93], v24, s[14:15]
	global_load_dwordx2 v[94:95], v24, s[16:17]
	global_load_dwordx2 v[96:97], v25, s[36:37] offset:1024
	global_load_dwordx2 v[98:99], v25, s[36:37] offset:1792
	global_load_dwordx4 v[100:103], v26, s[4:5]
	s_mul_i32 s8, s6, 3
	v_add_u32_e32 v121, s8, v2
	v_min_u32_e32 v20, s11, v121
	v_mul_hi_u32 v21, v20, s26
	v_lshrrev_b32_e32 v21, 6, v21
	v_mul_u32_u24_e32 v22, 0x60, v21
	v_sub_u32_e32 v22, v20, v22
	v_lshlrev_b32_e32 v23, 3, v22
	v_mul_u32_u24_e32 v24, 0x300, v21
	v_add_u32_e32 v24, v24, v23
	v_mul_lo_u32 v25, v21, s67
	v_add3_u32 v25, v25, v23, s61
	v_lshlrev_b32_e32 v26, 4, v22
	v_lshlrev_b32_e32 v27, 11, v21
	v_add_u32_e32 v27, 0x2a6f000, v27
	v_add_u32_e32 v120, v27, v23
	global_load_dwordx2 v[108:109], v24, s[14:15]
	global_load_dwordx2 v[110:111], v24, s[16:17]
	global_load_dwordx2 v[112:113], v25, s[36:37] offset:1024
	global_load_dwordx2 v[114:115], v25, s[36:37] offset:1792
	global_load_dwordx4 v[116:119], v26, s[4:5]
	s_mul_i32 s8, s6, 4
	v_add_u32_e32 v137, s8, v2
	v_min_u32_e32 v20, s11, v137
	v_mul_hi_u32 v21, v20, s26
	v_lshrrev_b32_e32 v21, 6, v21
	v_mul_u32_u24_e32 v22, 0x60, v21
	v_sub_u32_e32 v22, v20, v22
	v_lshlrev_b32_e32 v23, 3, v22
	v_mul_u32_u24_e32 v24, 0x300, v21
	v_add_u32_e32 v24, v24, v23
	v_mul_lo_u32 v25, v21, s67
	v_add3_u32 v25, v25, v23, s61
	v_lshlrev_b32_e32 v26, 4, v22
	v_lshlrev_b32_e32 v27, 11, v21
	v_add_u32_e32 v27, 0x2a6f000, v27
	v_add_u32_e32 v136, v27, v23
	global_load_dwordx2 v[124:125], v24, s[14:15]
	global_load_dwordx2 v[126:127], v24, s[16:17]
	global_load_dwordx2 v[128:129], v25, s[36:37] offset:1024
	global_load_dwordx2 v[130:131], v25, s[36:37] offset:1792
	global_load_dwordx4 v[132:135], v26, s[4:5]
; DI float bflo(unsigned v) { return __uint_as_float(v << 16); }
; DI float bfhi(unsigned v) { return __uint_as_float(v & 0xffff0000u); }
; DI float silu_f(float v) { return v / (1.f + __expf(-v)); }
; DI float sigmoid_f(float v) { return 1.f / (1.f + __expf(-v)); }
; DI void st_bf4(u16* dst, float a, float b, float c, float d) { uint2 u = {pk2(a, b), pk2(c, d)}; *(uint2*)dst = u; }
; DI void phase_fin(const Params& p, int layer, const VBC& vc) {
;     ...
;     for (long idx = (long)VBID * 256 + tid; idx < (long)ntok * 96; idx += (long)VGRID * 256) {
;         const int tok = (int)(idx / 96), rem = (int)(idx % 96), hd = rem >> 4, q = rem & 15, col = hd * 64 + q * 4;
;         uint2 a = *(const uint2*)(HF + (size_t)tok * 384 + col), bq = *(const uint2*)(HB + (size_t)tok * 384 + col);
;         float s0 = bflo(a.x) + bflo(bq.x), s1 = bfhi(a.x) + bfhi(bq.x), s2 = bflo(a.y) + bflo(bq.y), s3 = bfhi(a.y) + bfhi(bq.y);
;         float ss = s0 * s0 + s1 * s1 + s2 * s2 + s3 * s3;
;         ss += __shfl_xor(ss, 1); ss += __shfl_xor(ss, 2); ss += __shfl_xor(ss, 4); ss += __shfl_xor(ss, 8);
;         const float rs = rsqrtf(ss * (1.f / 64.f) + LN_EPS);
;         float4 gv = *(const float4*)(gn + col);
;         uint2 o = *(const uint2*)(P + (size_t)tok * PC + P_OM + col), z = *(const uint2*)(P + (size_t)tok * PC + P_ZM + col);
;         st_bf4(Y + (size_t)tok * LDK + 640 + col,
;                s0 * rs * gv.x * sigmoid_f(bflo(o.x)) * silu_f(bflo(z.x)), s1 * rs * gv.y * sigmoid_f(bfhi(o.x)) * silu_f(bfhi(z.x)),
;                s2 * rs * gv.z * sigmoid_f(bflo(o.y)) * silu_f(bflo(z.y)), s3 * rs * gv.w * sigmoid_f(bfhi(o.y)) * silu_f(bfhi(z.y)));
;     }
.Lfin_top:
	v_cmp_gt_u32_e32 vcc, s0, v73
	s_cbranch_vccz .Lfin_done
	s_waitcnt vmcnt(20)
	v_mov_b64_e32 v[14:15], v[60:61]
	v_mov_b64_e32 v[18:19], v[62:63]
	v_mov_b64_e32 v[26:27], v[64:65]
	v_mov_b64_e32 v[24:25], v[66:67]
	v_lshlrev_b32_e32 v20, 16, v14
	v_and_b32_e32 v21, 0xffff0000, v14
	v_lshlrev_b32_e32 v0, 16, v26
	v_and_b32_e32 v9, 0xffff0000, v26
	v_mul_f32_e32 v0, 0xbfb8aa3b, v0
	v_mul_f32_e32 v9, 0xbfb8aa3b, v9
	v_exp_f32_e32 v28, v0
	v_exp_f32_e32 v29, v9
	v_lshlrev_b32_e32 v30, 16, v25
	v_and_b32_e32 v31, 0xffff0000, v25
	v_lshlrev_b32_e32 v10, 16, v27
	v_pk_add_f32 v[28:29], v[28:29], 1.0 op_sel_hi:[1,0]
	v_mul_f32_e32 v10, 0xbfb8aa3b, v10
	v_div_scale_f32 v25, s[12:13], v29, v29, 1.0
	v_rcp_f32_e32 v32, v25
	v_exp_f32_e32 v26, v10
	v_and_b32_e32 v10, 0xffff0000, v27
	v_mul_f32_e32 v10, 0xbfb8aa3b, v10
	v_fma_f32 v33, -v25, v32, 1.0
	v_fmac_f32_e32 v32, v33, v32
	v_div_scale_f32 v33, vcc, 1.0, v29, 1.0
	v_mul_f32_e32 v34, v33, v32
	v_fma_f32 v35, -v25, v34, v33
	v_fmac_f32_e32 v34, v35, v32
	v_fma_f32 v25, -v25, v34, v33
	v_exp_f32_e32 v27, v10
	v_div_fmas_f32 v25, v25, v32, v34
	v_div_fixup_f32 v29, v25, v29, 1.0
	v_div_scale_f32 v25, s[12:13], v28, v28, 1.0
	v_rcp_f32_e32 v32, v25
	v_lshlrev_b32_e32 v0, 16, v24
	v_and_b32_e32 v9, 0xffff0000, v24
	v_mul_f32_e32 v24, 0xbfb8aa3b, v0
	v_fma_f32 v33, -v25, v32, 1.0
	v_fmac_f32_e32 v32, v33, v32
	v_div_scale_f32 v33, vcc, 1.0, v28, 1.0
	v_mul_f32_e32 v34, v33, v32
	v_fma_f32 v35, -v25, v34, v33
	v_fmac_f32_e32 v34, v35, v32
	v_fma_f32 v25, -v25, v34, v33
	v_div_fmas_f32 v25, v25, v32, v34
	v_div_fixup_f32 v28, v25, v28, 1.0
	v_mul_f32_e32 v25, 0xbfb8aa3b, v9
	v_exp_f32_e32 v24, v24
	v_exp_f32_e32 v25, v25
	v_lshlrev_b32_e32 v22, 16, v18
	v_and_b32_e32 v23, 0xffff0000, v18
	v_lshlrev_b32_e32 v14, 16, v15
	v_pk_add_f32 v[24:25], v[24:25], 1.0 op_sel_hi:[1,0]
	v_lshlrev_b32_e32 v18, 16, v19
	v_div_scale_f32 v32, s[12:13], v25, v25, v9
	v_rcp_f32_e32 v33, v32
	v_and_b32_e32 v15, 0xffff0000, v15
	v_and_b32_e32 v19, 0xffff0000, v19
	v_pk_add_f32 v[20:21], v[20:21], v[22:23]
	v_fma_f32 v34, -v32, v33, 1.0
	v_fmac_f32_e32 v33, v34, v33
	v_div_scale_f32 v34, vcc, v9, v25, v9
	v_mul_f32_e32 v35, v34, v33
	v_fma_f32 v36, -v32, v35, v34
	v_fmac_f32_e32 v35, v36, v33
	v_fma_f32 v32, -v32, v35, v34
	v_div_fmas_f32 v32, v32, v33, v35
	v_div_fixup_f32 v25, v32, v25, v9
	v_div_scale_f32 v9, s[12:13], v24, v24, v0
	v_rcp_f32_e32 v32, v9
	v_pk_add_f32 v[14:15], v[14:15], v[18:19]
	v_pk_mul_f32 v[22:23], v[20:21], v[20:21]
	v_pk_mul_f32 v[18:19], v[14:15], v[14:15]
	v_fma_f32 v33, -v9, v32, 1.0
	v_fmac_f32_e32 v32, v33, v32
	v_div_scale_f32 v33, vcc, v0, v24, v0
	v_mul_f32_e32 v34, v33, v32
	v_fma_f32 v35, -v9, v34, v33
	v_fmac_f32_e32 v34, v35, v32
	v_fma_f32 v9, -v9, v34, v33
	v_div_fmas_f32 v9, v9, v32, v34
	v_div_fixup_f32 v24, v9, v24, v0
	v_add_f32_e32 v0, v22, v23
	v_add_f32_e32 v0, v0, v18
	v_add_f32_e32 v0, v19, v0
	s_nop 1
	v_add_f32_dpp v0, v0, v0 quad_perm:[1,0,3,2] row_mask:0xf bank_mask:0xf
	s_nop 1
	v_add_f32_dpp v0, v0, v0 quad_perm:[2,3,0,1] row_mask:0xf bank_mask:0xf
	s_nop 1
	v_add_f32_dpp v0, v0, v0 row_half_mirror row_mask:0xf bank_mask:0xf
	s_nop 1
	v_add_f32_dpp v0, v0, v0 row_mirror row_mask:0xf bank_mask:0xf
	v_fmamk_f32 v0, v0, 0x3c800000, v229
	v_cmp_gt_f32_e32 vcc, s25, v0
	v_mul_f32_e32 v9, 0x4b800000, v0
	s_nop 0
	v_cndmask_b32_e32 v0, v0, v9, vcc
	v_rsq_f32_e32 v0, v0
	s_nop 0
	v_mul_f32_e32 v9, 0x45800000, v0
	v_cndmask_b32_e32 v0, v0, v9, vcc
	v_pk_mul_f32 v[14:15], v[14:15], v[0:1] op_sel_hi:[1,0]
	v_pk_mul_f32 v[18:19], v[20:21], v[0:1] op_sel_hi:[1,0]
	v_mov_b64_e32 v[10:11], v[68:69]
	v_mov_b64_e32 v[12:13], v[70:71]
	v_pk_mul_f32 v[12:13], v[12:13], v[14:15]
	v_pk_add_f32 v[14:15], v[26:27], 1.0 op_sel_hi:[1,0]
	v_mul_f32_e32 v9, 0xbfb8aa3b, v30
	v_div_scale_f32 v0, s[12:13], v15, v15, 1.0
	v_pk_mul_f32 v[10:11], v[10:11], v[18:19]
	v_exp_f32_e32 v18, v9
	v_rcp_f32_e32 v9, v0
	v_pk_mul_f32 v[10:11], v[28:29], v[10:11]
	v_fma_f32 v19, -v0, v9, 1.0
	v_fmac_f32_e32 v9, v19, v9
	v_div_scale_f32 v19, vcc, 1.0, v15, 1.0
	v_mul_f32_e32 v20, v19, v9
	v_fma_f32 v21, -v0, v20, v19
	v_fmac_f32_e32 v20, v21, v9
	v_fma_f32 v0, -v0, v20, v19
	v_div_fmas_f32 v0, v0, v9, v20
	v_div_fixup_f32 v15, v0, v15, 1.0
	v_div_scale_f32 v0, s[12:13], v14, v14, 1.0
	v_rcp_f32_e32 v9, v0
	v_pk_mul_f32 v[10:11], v[24:25], v[10:11]
	v_fma_f32 v19, -v0, v9, 1.0
	v_fmac_f32_e32 v9, v19, v9
	v_div_scale_f32 v19, vcc, 1.0, v14, 1.0
	v_mul_f32_e32 v20, v19, v9
	v_fma_f32 v21, -v0, v20, v19
	v_fmac_f32_e32 v20, v21, v9
	v_fma_f32 v0, -v0, v20, v19
	v_div_fmas_f32 v0, v0, v9, v20
	v_div_fixup_f32 v14, v0, v14, 1.0
	v_mul_f32_e32 v0, 0xbfb8aa3b, v31
	v_exp_f32_e32 v19, v0
	v_pk_mul_f32 v[12:13], v[14:15], v[12:13]
	v_cvt_pk_bf16_f32 v10, v10, v11
	v_pk_add_f32 v[14:15], v[18:19], 1.0 op_sel_hi:[1,0]
	s_nop 0
	v_div_scale_f32 v0, s[12:13], v15, v15, v31
	v_rcp_f32_e32 v9, v0
	s_nop 0
	v_fma_f32 v18, -v0, v9, 1.0
	v_fmac_f32_e32 v9, v18, v9
	v_div_scale_f32 v18, vcc, v31, v15, v31
	v_mul_f32_e32 v19, v18, v9
	v_fma_f32 v20, -v0, v19, v18
	v_fmac_f32_e32 v19, v20, v9
	v_fma_f32 v0, -v0, v19, v18
	v_div_fmas_f32 v0, v0, v9, v19
	v_div_fixup_f32 v15, v0, v15, v31
	v_div_scale_f32 v0, s[12:13], v14, v14, v30
	v_rcp_f32_e32 v9, v0
	s_nop 0
	v_fma_f32 v18, -v0, v9, 1.0
	v_fmac_f32_e32 v9, v18, v9
	v_div_scale_f32 v18, vcc, v30, v14, v30
	v_mul_f32_e32 v19, v18, v9
	v_fma_f32 v20, -v0, v19, v18
	v_fmac_f32_e32 v19, v20, v9
	v_fma_f32 v0, -v0, v19, v18
	v_div_fmas_f32 v0, v0, v9, v19
	v_div_fixup_f32 v14, v0, v14, v30
	v_pk_mul_f32 v[12:13], v[14:15], v[12:13]
	s_nop 0
	v_cvt_pk_bf16_f32 v11, v12, v13
	s_mov_b64 s[12:13], exec
	v_cmp_gt_u32_e32 vcc, s0, v73
	s_and_b64 exec, s[12:13], vcc
	global_store_dwordx2 v72, v[10:11], s[30:31] offset:1792
	s_mov_b64 exec, s[12:13]
	s_mul_i32 s8, s6, 5
	v_add_u32_e32 v73, s8, v2
	v_min_u32_e32 v20, s11, v73
	v_mul_hi_u32 v21, v20, s26
	v_lshrrev_b32_e32 v21, 6, v21
	v_mul_u32_u24_e32 v22, 0x60, v21
	v_sub_u32_e32 v22, v20, v22
	v_lshlrev_b32_e32 v23, 3, v22
	v_mul_u32_u24_e32 v24, 0x300, v21
	v_add_u32_e32 v24, v24, v23
	v_mul_lo_u32 v25, v21, s67
	v_add3_u32 v25, v25, v23, s61
	v_lshlrev_b32_e32 v26, 4, v22
	v_lshlrev_b32_e32 v27, 11, v21
	v_add_u32_e32 v27, 0x2a6f000, v27
	v_add_u32_e32 v72, v27, v23
	global_load_dwordx2 v[60:61], v24, s[14:15]
	global_load_dwordx2 v[62:63], v24, s[16:17]
	global_load_dwordx2 v[64:65], v25, s[36:37] offset:1024
	global_load_dwordx2 v[66:67], v25, s[36:37] offset:1792
	global_load_dwordx4 v[68:71], v26, s[4:5]
	v_cmp_gt_u32_e32 vcc, s0, v89
	s_cbranch_vccz .Lfin_done
; DI float bflo(unsigned v) { return __uint_as_float(v << 16); }
; DI float bfhi(unsigned v) { return __uint_as_float(v & 0xffff0000u); }
; DI float silu_f(float v) { return v / (1.f + __expf(-v)); }
; DI float sigmoid_f(float v) { return 1.f / (1.f + __expf(-v)); }
; DI void st_bf4(u16* dst, float a, float b, float c, float d) { uint2 u = {pk2(a, b), pk2(c, d)}; *(uint2*)dst = u; }
; DI void phase_fin(const Params& p, int layer, const VBC& vc) {
;     ...
;     for (long idx = (long)VBID * 256 + tid; idx < (long)ntok * 96; idx += (long)VGRID * 256) {
;         const int tok = (int)(idx / 96), rem = (int)(idx % 96), hd = rem >> 4, q = rem & 15, col = hd * 64 + q * 4;
;         uint2 a = *(const uint2*)(HF + (size_t)tok * 384 + col), bq = *(const uint2*)(HB + (size_t)tok * 384 + col);
;         float s0 = bflo(a.x) + bflo(bq.x), s1 = bfhi(a.x) + bfhi(bq.x), s2 = bflo(a.y) + bflo(bq.y), s3 = bfhi(a.y) + bfhi(bq.y);
;         float ss = s0 * s0 + s1 * s1 + s2 * s2 + s3 * s3;
;         ss += __shfl_xor(ss, 1); ss += __shfl_xor(ss, 2); ss += __shfl_xor(ss, 4); ss += __shfl_xor(ss, 8);
;         const float rs = rsqrtf(ss * (1.f / 64.f) + LN_EPS);
;         float4 gv = *(const float4*)(gn + col);
;         uint2 o = *(const uint2*)(P + (size_t)tok * PC + P_OM + col), z = *(const uint2*)(P + (size_t)tok * PC + P_ZM + col);
;         st_bf4(Y + (size_t)tok * LDK + 640 + col,
;                s0 * rs * gv.x * sigmoid_f(bflo(o.x)) * silu_f(bflo(z.x)), s1 * rs * gv.y * sigmoid_f(bfhi(o.x)) * silu_f(bfhi(z.x)),
;                s2 * rs * gv.z * sigmoid_f(bflo(o.y)) * silu_f(bflo(z.y)), s3 * rs * gv.w * sigmoid_f(bfhi(o.y)) * silu_f(bfhi(z.y)));
;     }
	s_waitcnt vmcnt(20)
	v_mov_b64_e32 v[14:15], v[76:77]
	v_mov_b64_e32 v[18:19], v[78:79]
	v_mov_b64_e32 v[26:27], v[80:81]
	v_mov_b64_e32 v[24:25], v[82:83]
	v_lshlrev_b32_e32 v20, 16, v14
	v_and_b32_e32 v21, 0xffff0000, v14
	v_lshlrev_b32_e32 v0, 16, v26
	v_and_b32_e32 v9, 0xffff0000, v26
	v_mul_f32_e32 v0, 0xbfb8aa3b, v0
	v_mul_f32_e32 v9, 0xbfb8aa3b, v9
	v_exp_f32_e32 v28, v0
	v_exp_f32_e32 v29, v9
	v_lshlrev_b32_e32 v30, 16, v25
	v_and_b32_e32 v31, 0xffff0000, v25
	v_lshlrev_b32_e32 v10, 16, v27
	v_pk_add_f32 v[28:29], v[28:29], 1.0 op_sel_hi:[1,0]
	v_mul_f32_e32 v10, 0xbfb8aa3b, v10
	v_div_scale_f32 v25, s[12:13], v29, v29, 1.0
	v_rcp_f32_e32 v32, v25
	v_exp_f32_e32 v26, v10
	v_and_b32_e32 v10, 0xffff0000, v27
	v_mul_f32_e32 v10, 0xbfb8aa3b, v10
	v_fma_f32 v33, -v25, v32, 1.0
	v_fmac_f32_e32 v32, v33, v32
	v_div_scale_f32 v33, vcc, 1.0, v29, 1.0
	v_mul_f32_e32 v34, v33, v32
	v_fma_f32 v35, -v25, v34, v33
	v_fmac_f32_e32 v34, v35, v32
	v_fma_f32 v25, -v25, v34, v33
	v_exp_f32_e32 v27, v10
	v_div_fmas_f32 v25, v25, v32, v34
	v_div_fixup_f32 v29, v25, v29, 1.0
	v_div_scale_f32 v25, s[12:13], v28, v28, 1.0
	v_rcp_f32_e32 v32, v25
	v_lshlrev_b32_e32 v0, 16, v24
	v_and_b32_e32 v9, 0xffff0000, v24
	v_mul_f32_e32 v24, 0xbfb8aa3b, v0
	v_fma_f32 v33, -v25, v32, 1.0
	v_fmac_f32_e32 v32, v33, v32
	v_div_scale_f32 v33, vcc, 1.0, v28, 1.0
	v_mul_f32_e32 v34, v33, v32
	v_fma_f32 v35, -v25, v34, v33
	v_fmac_f32_e32 v34, v35, v32
	v_fma_f32 v25, -v25, v34, v33
	v_div_fmas_f32 v25, v25, v32, v34
	v_div_fixup_f32 v28, v25, v28, 1.0
	v_mul_f32_e32 v25, 0xbfb8aa3b, v9
	v_exp_f32_e32 v24, v24
	v_exp_f32_e32 v25, v25
	v_lshlrev_b32_e32 v22, 16, v18
	v_and_b32_e32 v23, 0xffff0000, v18
	v_lshlrev_b32_e32 v14, 16, v15
	v_pk_add_f32 v[24:25], v[24:25], 1.0 op_sel_hi:[1,0]
	v_lshlrev_b32_e32 v18, 16, v19
	v_div_scale_f32 v32, s[12:13], v25, v25, v9
	v_rcp_f32_e32 v33, v32
	v_and_b32_e32 v15, 0xffff0000, v15
	v_and_b32_e32 v19, 0xffff0000, v19
	v_pk_add_f32 v[20:21], v[20:21], v[22:23]
	v_fma_f32 v34, -v32, v33, 1.0
	v_fmac_f32_e32 v33, v34, v33
	v_div_scale_f32 v34, vcc, v9, v25, v9
	v_mul_f32_e32 v35, v34, v33
	v_fma_f32 v36, -v32, v35, v34
	v_fmac_f32_e32 v35, v36, v33
	v_fma_f32 v32, -v32, v35, v34
	v_div_fmas_f32 v32, v32, v33, v35
	v_div_fixup_f32 v25, v32, v25, v9
	v_div_scale_f32 v9, s[12:13], v24, v24, v0
	v_rcp_f32_e32 v32, v9
	v_pk_add_f32 v[14:15], v[14:15], v[18:19]
	v_pk_mul_f32 v[22:23], v[20:21], v[20:21]
	v_pk_mul_f32 v[18:19], v[14:15], v[14:15]
	v_fma_f32 v33, -v9, v32, 1.0
	v_fmac_f32_e32 v32, v33, v32
	v_div_scale_f32 v33, vcc, v0, v24, v0
	v_mul_f32_e32 v34, v33, v32
	v_fma_f32 v35, -v9, v34, v33
	v_fmac_f32_e32 v34, v35, v32
	v_fma_f32 v9, -v9, v34, v33
	v_div_fmas_f32 v9, v9, v32, v34
	v_div_fixup_f32 v24, v9, v24, v0
	v_add_f32_e32 v0, v22, v23
	v_add_f32_e32 v0, v0, v18
	v_add_f32_e32 v0, v19, v0
	s_nop 1
	v_add_f32_dpp v0, v0, v0 quad_perm:[1,0,3,2] row_mask:0xf bank_mask:0xf
	s_nop 1
	v_add_f32_dpp v0, v0, v0 quad_perm:[2,3,0,1] row_mask:0xf bank_mask:0xf
	s_nop 1
	v_add_f32_dpp v0, v0, v0 row_half_mirror row_mask:0xf bank_mask:0xf
	s_nop 1
	v_add_f32_dpp v0, v0, v0 row_mirror row_mask:0xf bank_mask:0xf
	v_fmamk_f32 v0, v0, 0x3c800000, v229
	v_cmp_gt_f32_e32 vcc, s25, v0
	v_mul_f32_e32 v9, 0x4b800000, v0
	s_nop 0
	v_cndmask_b32_e32 v0, v0, v9, vcc
	v_rsq_f32_e32 v0, v0
	s_nop 0
	v_mul_f32_e32 v9, 0x45800000, v0
	v_cndmask_b32_e32 v0, v0, v9, vcc
	v_pk_mul_f32 v[14:15], v[14:15], v[0:1] op_sel_hi:[1,0]
	v_pk_mul_f32 v[18:19], v[20:21], v[0:1] op_sel_hi:[1,0]
	v_mov_b64_e32 v[10:11], v[84:85]
	v_mov_b64_e32 v[12:13], v[86:87]
	v_pk_mul_f32 v[12:13], v[12:13], v[14:15]
	v_pk_add_f32 v[14:15], v[26:27], 1.0 op_sel_hi:[1,0]
	v_mul_f32_e32 v9, 0xbfb8aa3b, v30
	v_div_scale_f32 v0, s[12:13], v15, v15, 1.0
	v_pk_mul_f32 v[10:11], v[10:11], v[18:19]
	v_exp_f32_e32 v18, v9
	v_rcp_f32_e32 v9, v0
	v_pk_mul_f32 v[10:11], v[28:29], v[10:11]
	v_fma_f32 v19, -v0, v9, 1.0
	v_fmac_f32_e32 v9, v19, v9
	v_div_scale_f32 v19, vcc, 1.0, v15, 1.0
	v_mul_f32_e32 v20, v19, v9
	v_fma_f32 v21, -v0, v20, v19
	v_fmac_f32_e32 v20, v21, v9
	v_fma_f32 v0, -v0, v20, v19
	v_div_fmas_f32 v0, v0, v9, v20
	v_div_fixup_f32 v15, v0, v15, 1.0
	v_div_scale_f32 v0, s[12:13], v14, v14, 1.0
	v_rcp_f32_e32 v9, v0
	v_pk_mul_f32 v[10:11], v[24:25], v[10:11]
	v_fma_f32 v19, -v0, v9, 1.0
	v_fmac_f32_e32 v9, v19, v9
	v_div_scale_f32 v19, vcc, 1.0, v14, 1.0
	v_mul_f32_e32 v20, v19, v9
	v_fma_f32 v21, -v0, v20, v19
	v_fmac_f32_e32 v20, v21, v9
	v_fma_f32 v0, -v0, v20, v19
	v_div_fmas_f32 v0, v0, v9, v20
	v_div_fixup_f32 v14, v0, v14, 1.0
	v_mul_f32_e32 v0, 0xbfb8aa3b, v31
	v_exp_f32_e32 v19, v0
	v_pk_mul_f32 v[12:13], v[14:15], v[12:13]
	v_cvt_pk_bf16_f32 v10, v10, v11
	v_pk_add_f32 v[14:15], v[18:19], 1.0 op_sel_hi:[1,0]
	s_nop 0
	v_div_scale_f32 v0, s[12:13], v15, v15, v31
	v_rcp_f32_e32 v9, v0
	s_nop 0
	v_fma_f32 v18, -v0, v9, 1.0
	v_fmac_f32_e32 v9, v18, v9
	v_div_scale_f32 v18, vcc, v31, v15, v31
	v_mul_f32_e32 v19, v18, v9
	v_fma_f32 v20, -v0, v19, v18
	v_fmac_f32_e32 v19, v20, v9
	v_fma_f32 v0, -v0, v19, v18
	v_div_fmas_f32 v0, v0, v9, v19
	v_div_fixup_f32 v15, v0, v15, v31
	v_div_scale_f32 v0, s[12:13], v14, v14, v30
	v_rcp_f32_e32 v9, v0
	s_nop 0
	v_fma_f32 v18, -v0, v9, 1.0
	v_fmac_f32_e32 v9, v18, v9
	v_div_scale_f32 v18, vcc, v30, v14, v30
	v_mul_f32_e32 v19, v18, v9
	v_fma_f32 v20, -v0, v19, v18
	v_fmac_f32_e32 v19, v20, v9
	v_fma_f32 v0, -v0, v19, v18
	v_div_fmas_f32 v0, v0, v9, v19
	v_div_fixup_f32 v14, v0, v14, v30
	v_pk_mul_f32 v[12:13], v[14:15], v[12:13]
	s_nop 0
	v_cvt_pk_bf16_f32 v11, v12, v13
	s_mov_b64 s[12:13], exec
	v_cmp_gt_u32_e32 vcc, s0, v89
	s_and_b64 exec, s[12:13], vcc
	global_store_dwordx2 v88, v[10:11], s[30:31] offset:1792
	s_mov_b64 exec, s[12:13]
	s_mul_i32 s8, s6, 6
	v_add_u32_e32 v89, s8, v2
	v_min_u32_e32 v20, s11, v89
	v_mul_hi_u32 v21, v20, s26
	v_lshrrev_b32_e32 v21, 6, v21
	v_mul_u32_u24_e32 v22, 0x60, v21
	v_sub_u32_e32 v22, v20, v22
	v_lshlrev_b32_e32 v23, 3, v22
	v_mul_u32_u24_e32 v24, 0x300, v21
	v_add_u32_e32 v24, v24, v23
	v_mul_lo_u32 v25, v21, s67
	v_add3_u32 v25, v25, v23, s61
	v_lshlrev_b32_e32 v26, 4, v22
	v_lshlrev_b32_e32 v27, 11, v21
	v_add_u32_e32 v27, 0x2a6f000, v27
	v_add_u32_e32 v88, v27, v23
	global_load_dwordx2 v[76:77], v24, s[14:15]
	global_load_dwordx2 v[78:79], v24, s[16:17]
	global_load_dwordx2 v[80:81], v25, s[36:37] offset:1024
	global_load_dwordx2 v[82:83], v25, s[36:37] offset:1792
	global_load_dwordx4 v[84:87], v26, s[4:5]
	v_cmp_gt_u32_e32 vcc, s0, v105
	s_cbranch_vccz .Lfin_done
; DI float bflo(unsigned v) { return __uint_as_float(v << 16); }
; DI float bfhi(unsigned v) { return __uint_as_float(v & 0xffff0000u); }
; DI float silu_f(float v) { return v / (1.f + __expf(-v)); }
; DI float sigmoid_f(float v) { return 1.f / (1.f + __expf(-v)); }
; DI void st_bf4(u16* dst, float a, float b, float c, float d) { uint2 u = {pk2(a, b), pk2(c, d)}; *(uint2*)dst = u; }
; DI void phase_fin(const Params& p, int layer, const VBC& vc) {
;     ...
;     for (long idx = (long)VBID * 256 + tid; idx < (long)ntok * 96; idx += (long)VGRID * 256) {
;         const int tok = (int)(idx / 96), rem = (int)(idx % 96), hd = rem >> 4, q = rem & 15, col = hd * 64 + q * 4;
;         uint2 a = *(const uint2*)(HF + (size_t)tok * 384 + col), bq = *(const uint2*)(HB + (size_t)tok * 384 + col);
;         float s0 = bflo(a.x) + bflo(bq.x), s1 = bfhi(a.x) + bfhi(bq.x), s2 = bflo(a.y) + bflo(bq.y), s3 = bfhi(a.y) + bfhi(bq.y);
;         float ss = s0 * s0 + s1 * s1 + s2 * s2 + s3 * s3;
;         ss += __shfl_xor(ss, 1); ss += __shfl_xor(ss, 2); ss += __shfl_xor(ss, 4); ss += __shfl_xor(ss, 8);
;         const float rs = rsqrtf(ss * (1.f / 64.f) + LN_EPS);
;         float4 gv = *(const float4*)(gn + col);
;         uint2 o = *(const uint2*)(P + (size_t)tok * PC + P_OM + col), z = *(const uint2*)(P + (size_t)tok * PC + P_ZM + col);
;         st_bf4(Y + (size_t)tok * LDK + 640 + col,
;                s0 * rs * gv.x * sigmoid_f(bflo(o.x)) * silu_f(bflo(z.x)), s1 * rs * gv.y * sigmoid_f(bfhi(o.x)) * silu_f(bfhi(z.x)),
;                s2 * rs * gv.z * sigmoid_f(bflo(o.y)) * silu_f(bflo(z.y)), s3 * rs * gv.w * sigmoid_f(bfhi(o.y)) * silu_f(bfhi(z.y)));
;     }
	s_waitcnt vmcnt(20)
	v_mov_b64_e32 v[14:15], v[92:93]
	v_mov_b64_e32 v[18:19], v[94:95]
	v_mov_b64_e32 v[26:27], v[96:97]
	v_mov_b64_e32 v[24:25], v[98:99]
	v_lshlrev_b32_e32 v20, 16, v14
	v_and_b32_e32 v21, 0xffff0000, v14
	v_lshlrev_b32_e32 v0, 16, v26
	v_and_b32_e32 v9, 0xffff0000, v26
	v_mul_f32_e32 v0, 0xbfb8aa3b, v0
	v_mul_f32_e32 v9, 0xbfb8aa3b, v9
	v_exp_f32_e32 v28, v0
	v_exp_f32_e32 v29, v9
	v_lshlrev_b32_e32 v30, 16, v25
	v_and_b32_e32 v31, 0xffff0000, v25
	v_lshlrev_b32_e32 v10, 16, v27
	v_pk_add_f32 v[28:29], v[28:29], 1.0 op_sel_hi:[1,0]
	v_mul_f32_e32 v10, 0xbfb8aa3b, v10
	v_div_scale_f32 v25, s[12:13], v29, v29, 1.0
	v_rcp_f32_e32 v32, v25
	v_exp_f32_e32 v26, v10
	v_and_b32_e32 v10, 0xffff0000, v27
	v_mul_f32_e32 v10, 0xbfb8aa3b, v10
	v_fma_f32 v33, -v25, v32, 1.0
	v_fmac_f32_e32 v32, v33, v32
	v_div_scale_f32 v33, vcc, 1.0, v29, 1.0
	v_mul_f32_e32 v34, v33, v32
	v_fma_f32 v35, -v25, v34, v33
	v_fmac_f32_e32 v34, v35, v32
	v_fma_f32 v25, -v25, v34, v33
	v_exp_f32_e32 v27, v10
	v_div_fmas_f32 v25, v25, v32, v34
	v_div_fixup_f32 v29, v25, v29, 1.0
	v_div_scale_f32 v25, s[12:13], v28, v28, 1.0
	v_rcp_f32_e32 v32, v25
	v_lshlrev_b32_e32 v0, 16, v24
	v_and_b32_e32 v9, 0xffff0000, v24
	v_mul_f32_e32 v24, 0xbfb8aa3b, v0
	v_fma_f32 v33, -v25, v32, 1.0
	v_fmac_f32_e32 v32, v33, v32
	v_div_scale_f32 v33, vcc, 1.0, v28, 1.0
	v_mul_f32_e32 v34, v33, v32
	v_fma_f32 v35, -v25, v34, v33
	v_fmac_f32_e32 v34, v35, v32
	v_fma_f32 v25, -v25, v34, v33
	v_div_fmas_f32 v25, v25, v32, v34
	v_div_fixup_f32 v28, v25, v28, 1.0
	v_mul_f32_e32 v25, 0xbfb8aa3b, v9
	v_exp_f32_e32 v24, v24
	v_exp_f32_e32 v25, v25
	v_lshlrev_b32_e32 v22, 16, v18
	v_and_b32_e32 v23, 0xffff0000, v18
	v_lshlrev_b32_e32 v14, 16, v15
	v_pk_add_f32 v[24:25], v[24:25], 1.0 op_sel_hi:[1,0]
	v_lshlrev_b32_e32 v18, 16, v19
	v_div_scale_f32 v32, s[12:13], v25, v25, v9
	v_rcp_f32_e32 v33, v32
	v_and_b32_e32 v15, 0xffff0000, v15
	v_and_b32_e32 v19, 0xffff0000, v19
	v_pk_add_f32 v[20:21], v[20:21], v[22:23]
	v_fma_f32 v34, -v32, v33, 1.0
	v_fmac_f32_e32 v33, v34, v33
	v_div_scale_f32 v34, vcc, v9, v25, v9
	v_mul_f32_e32 v35, v34, v33
	v_fma_f32 v36, -v32, v35, v34
	v_fmac_f32_e32 v35, v36, v33
	v_fma_f32 v32, -v32, v35, v34
	v_div_fmas_f32 v32, v32, v33, v35
	v_div_fixup_f32 v25, v32, v25, v9
	v_div_scale_f32 v9, s[12:13], v24, v24, v0
	v_rcp_f32_e32 v32, v9
	v_pk_add_f32 v[14:15], v[14:15], v[18:19]
	v_pk_mul_f32 v[22:23], v[20:21], v[20:21]
	v_pk_mul_f32 v[18:19], v[14:15], v[14:15]
	v_fma_f32 v33, -v9, v32, 1.0
	v_fmac_f32_e32 v32, v33, v32
	v_div_scale_f32 v33, vcc, v0, v24, v0
	v_mul_f32_e32 v34, v33, v32
	v_fma_f32 v35, -v9, v34, v33
	v_fmac_f32_e32 v34, v35, v32
	v_fma_f32 v9, -v9, v34, v33
	v_div_fmas_f32 v9, v9, v32, v34
	v_div_fixup_f32 v24, v9, v24, v0
	v_add_f32_e32 v0, v22, v23
	v_add_f32_e32 v0, v0, v18
	v_add_f32_e32 v0, v19, v0
	s_nop 1
	v_add_f32_dpp v0, v0, v0 quad_perm:[1,0,3,2] row_mask:0xf bank_mask:0xf
	s_nop 1
	v_add_f32_dpp v0, v0, v0 quad_perm:[2,3,0,1] row_mask:0xf bank_mask:0xf
	s_nop 1
	v_add_f32_dpp v0, v0, v0 row_half_mirror row_mask:0xf bank_mask:0xf
	s_nop 1
	v_add_f32_dpp v0, v0, v0 row_mirror row_mask:0xf bank_mask:0xf
	v_fmamk_f32 v0, v0, 0x3c800000, v229
	v_cmp_gt_f32_e32 vcc, s25, v0
	v_mul_f32_e32 v9, 0x4b800000, v0
	s_nop 0
	v_cndmask_b32_e32 v0, v0, v9, vcc
	v_rsq_f32_e32 v0, v0
	s_nop 0
	v_mul_f32_e32 v9, 0x45800000, v0
	v_cndmask_b32_e32 v0, v0, v9, vcc
	v_pk_mul_f32 v[14:15], v[14:15], v[0:1] op_sel_hi:[1,0]
	v_pk_mul_f32 v[18:19], v[20:21], v[0:1] op_sel_hi:[1,0]
	v_mov_b64_e32 v[10:11], v[100:101]
	v_mov_b64_e32 v[12:13], v[102:103]
	v_pk_mul_f32 v[12:13], v[12:13], v[14:15]
	v_pk_add_f32 v[14:15], v[26:27], 1.0 op_sel_hi:[1,0]
	v_mul_f32_e32 v9, 0xbfb8aa3b, v30
	v_div_scale_f32 v0, s[12:13], v15, v15, 1.0
	v_pk_mul_f32 v[10:11], v[10:11], v[18:19]
	v_exp_f32_e32 v18, v9
	v_rcp_f32_e32 v9, v0
	v_pk_mul_f32 v[10:11], v[28:29], v[10:11]
	v_fma_f32 v19, -v0, v9, 1.0
	v_fmac_f32_e32 v9, v19, v9
	v_div_scale_f32 v19, vcc, 1.0, v15, 1.0
	v_mul_f32_e32 v20, v19, v9
	v_fma_f32 v21, -v0, v20, v19
	v_fmac_f32_e32 v20, v21, v9
	v_fma_f32 v0, -v0, v20, v19
	v_div_fmas_f32 v0, v0, v9, v20
	v_div_fixup_f32 v15, v0, v15, 1.0
	v_div_scale_f32 v0, s[12:13], v14, v14, 1.0
	v_rcp_f32_e32 v9, v0
	v_pk_mul_f32 v[10:11], v[24:25], v[10:11]
	v_fma_f32 v19, -v0, v9, 1.0
	v_fmac_f32_e32 v9, v19, v9
	v_div_scale_f32 v19, vcc, 1.0, v14, 1.0
	v_mul_f32_e32 v20, v19, v9
	v_fma_f32 v21, -v0, v20, v19
	v_fmac_f32_e32 v20, v21, v9
	v_fma_f32 v0, -v0, v20, v19
	v_div_fmas_f32 v0, v0, v9, v20
	v_div_fixup_f32 v14, v0, v14, 1.0
	v_mul_f32_e32 v0, 0xbfb8aa3b, v31
	v_exp_f32_e32 v19, v0
	v_pk_mul_f32 v[12:13], v[14:15], v[12:13]
	v_cvt_pk_bf16_f32 v10, v10, v11
	v_pk_add_f32 v[14:15], v[18:19], 1.0 op_sel_hi:[1,0]
	s_nop 0
	v_div_scale_f32 v0, s[12:13], v15, v15, v31
	v_rcp_f32_e32 v9, v0
	s_nop 0
	v_fma_f32 v18, -v0, v9, 1.0
	v_fmac_f32_e32 v9, v18, v9
	v_div_scale_f32 v18, vcc, v31, v15, v31
	v_mul_f32_e32 v19, v18, v9
	v_fma_f32 v20, -v0, v19, v18
	v_fmac_f32_e32 v19, v20, v9
	v_fma_f32 v0, -v0, v19, v18
	v_div_fmas_f32 v0, v0, v9, v19
	v_div_fixup_f32 v15, v0, v15, v31
	v_div_scale_f32 v0, s[12:13], v14, v14, v30
	v_rcp_f32_e32 v9, v0
	s_nop 0
	v_fma_f32 v18, -v0, v9, 1.0
	v_fmac_f32_e32 v9, v18, v9
	v_div_scale_f32 v18, vcc, v30, v14, v30
	v_mul_f32_e32 v19, v18, v9
	v_fma_f32 v20, -v0, v19, v18
	v_fmac_f32_e32 v19, v20, v9
	v_fma_f32 v0, -v0, v19, v18
	v_div_fmas_f32 v0, v0, v9, v19
	v_div_fixup_f32 v14, v0, v14, v30
	v_pk_mul_f32 v[12:13], v[14:15], v[12:13]
	s_nop 0
	v_cvt_pk_bf16_f32 v11, v12, v13
	s_mov_b64 s[12:13], exec
	v_cmp_gt_u32_e32 vcc, s0, v105
	s_and_b64 exec, s[12:13], vcc
	global_store_dwordx2 v104, v[10:11], s[30:31] offset:1792
	s_mov_b64 exec, s[12:13]
	s_mul_i32 s8, s6, 7
	v_add_u32_e32 v105, s8, v2
	v_min_u32_e32 v20, s11, v105
	v_mul_hi_u32 v21, v20, s26
	v_lshrrev_b32_e32 v21, 6, v21
	v_mul_u32_u24_e32 v22, 0x60, v21
	v_sub_u32_e32 v22, v20, v22
	v_lshlrev_b32_e32 v23, 3, v22
	v_mul_u32_u24_e32 v24, 0x300, v21
	v_add_u32_e32 v24, v24, v23
	v_mul_lo_u32 v25, v21, s67
	v_add3_u32 v25, v25, v23, s61
	v_lshlrev_b32_e32 v26, 4, v22
	v_lshlrev_b32_e32 v27, 11, v21
	v_add_u32_e32 v27, 0x2a6f000, v27
	v_add_u32_e32 v104, v27, v23
	global_load_dwordx2 v[92:93], v24, s[14:15]
	global_load_dwordx2 v[94:95], v24, s[16:17]
	global_load_dwordx2 v[96:97], v25, s[36:37] offset:1024
	global_load_dwordx2 v[98:99], v25, s[36:37] offset:1792
	global_load_dwordx4 v[100:103], v26, s[4:5]
	v_cmp_gt_u32_e32 vcc, s0, v121
	s_cbranch_vccz .Lfin_done
; DI float bflo(unsigned v) { return __uint_as_float(v << 16); }
; DI float bfhi(unsigned v) { return __uint_as_float(v & 0xffff0000u); }
; DI float silu_f(float v) { return v / (1.f + __expf(-v)); }
; DI float sigmoid_f(float v) { return 1.f / (1.f + __expf(-v)); }
; DI void st_bf4(u16* dst, float a, float b, float c, float d) { uint2 u = {pk2(a, b), pk2(c, d)}; *(uint2*)dst = u; }
; DI void phase_fin(const Params& p, int layer, const VBC& vc) {
;     ...
;     for (long idx = (long)VBID * 256 + tid; idx < (long)ntok * 96; idx += (long)VGRID * 256) {
;         const int tok = (int)(idx / 96), rem = (int)(idx % 96), hd = rem >> 4, q = rem & 15, col = hd * 64 + q * 4;
;         uint2 a = *(const uint2*)(HF + (size_t)tok * 384 + col), bq = *(const uint2*)(HB + (size_t)tok * 384 + col);
;         float s0 = bflo(a.x) + bflo(bq.x), s1 = bfhi(a.x) + bfhi(bq.x), s2 = bflo(a.y) + bflo(bq.y), s3 = bfhi(a.y) + bfhi(bq.y);
;         float ss = s0 * s0 + s1 * s1 + s2 * s2 + s3 * s3;
;         ss += __shfl_xor(ss, 1); ss += __shfl_xor(ss, 2); ss += __shfl_xor(ss, 4); ss += __shfl_xor(ss, 8);
;         const float rs = rsqrtf(ss * (1.f / 64.f) + LN_EPS);
;         float4 gv = *(const float4*)(gn + col);
;         uint2 o = *(const uint2*)(P + (size_t)tok * PC + P_OM + col), z = *(const uint2*)(P + (size_t)tok * PC + P_ZM + col);
;         st_bf4(Y + (size_t)tok * LDK + 640 + col,
;                s0 * rs * gv.x * sigmoid_f(bflo(o.x)) * silu_f(bflo(z.x)), s1 * rs * gv.y * sigmoid_f(bfhi(o.x)) * silu_f(bfhi(z.x)),
;                s2 * rs * gv.z * sigmoid_f(bflo(o.y)) * silu_f(bflo(z.y)), s3 * rs * gv.w * sigmoid_f(bfhi(o.y)) * silu_f(bfhi(z.y)));
;     }
	s_waitcnt vmcnt(20)
	v_mov_b64_e32 v[14:15], v[108:109]
	v_mov_b64_e32 v[18:19], v[110:111]
	v_mov_b64_e32 v[26:27], v[112:113]
	v_mov_b64_e32 v[24:25], v[114:115]
	v_lshlrev_b32_e32 v20, 16, v14
	v_and_b32_e32 v21, 0xffff0000, v14
	v_lshlrev_b32_e32 v0, 16, v26
	v_and_b32_e32 v9, 0xffff0000, v26
	v_mul_f32_e32 v0, 0xbfb8aa3b, v0
	v_mul_f32_e32 v9, 0xbfb8aa3b, v9
	v_exp_f32_e32 v28, v0
	v_exp_f32_e32 v29, v9
	v_lshlrev_b32_e32 v30, 16, v25
	v_and_b32_e32 v31, 0xffff0000, v25
	v_lshlrev_b32_e32 v10, 16, v27
	v_pk_add_f32 v[28:29], v[28:29], 1.0 op_sel_hi:[1,0]
	v_mul_f32_e32 v10, 0xbfb8aa3b, v10
	v_div_scale_f32 v25, s[12:13], v29, v29, 1.0
	v_rcp_f32_e32 v32, v25
	v_exp_f32_e32 v26, v10
	v_and_b32_e32 v10, 0xffff0000, v27
	v_mul_f32_e32 v10, 0xbfb8aa3b, v10
	v_fma_f32 v33, -v25, v32, 1.0
	v_fmac_f32_e32 v32, v33, v32
	v_div_scale_f32 v33, vcc, 1.0, v29, 1.0
	v_mul_f32_e32 v34, v33, v32
	v_fma_f32 v35, -v25, v34, v33
	v_fmac_f32_e32 v34, v35, v32
	v_fma_f32 v25, -v25, v34, v33
	v_exp_f32_e32 v27, v10
	v_div_fmas_f32 v25, v25, v32, v34
	v_div_fixup_f32 v29, v25, v29, 1.0
	v_div_scale_f32 v25, s[12:13], v28, v28, 1.0
	v_rcp_f32_e32 v32, v25
	v_lshlrev_b32_e32 v0, 16, v24
	v_and_b32_e32 v9, 0xffff0000, v24
	v_mul_f32_e32 v24, 0xbfb8aa3b, v0
	v_fma_f32 v33, -v25, v32, 1.0
	v_fmac_f32_e32 v32, v33, v32
	v_div_scale_f32 v33, vcc, 1.0, v28, 1.0
	v_mul_f32_e32 v34, v33, v32
	v_fma_f32 v35, -v25, v34, v33
	v_fmac_f32_e32 v34, v35, v32
	v_fma_f32 v25, -v25, v34, v33
	v_div_fmas_f32 v25, v25, v32, v34
	v_div_fixup_f32 v28, v25, v28, 1.0
	v_mul_f32_e32 v25, 0xbfb8aa3b, v9
	v_exp_f32_e32 v24, v24
	v_exp_f32_e32 v25, v25
	v_lshlrev_b32_e32 v22, 16, v18
	v_and_b32_e32 v23, 0xffff0000, v18
	v_lshlrev_b32_e32 v14, 16, v15
	v_pk_add_f32 v[24:25], v[24:25], 1.0 op_sel_hi:[1,0]
	v_lshlrev_b32_e32 v18, 16, v19
	v_div_scale_f32 v32, s[12:13], v25, v25, v9
	v_rcp_f32_e32 v33, v32
	v_and_b32_e32 v15, 0xffff0000, v15
	v_and_b32_e32 v19, 0xffff0000, v19
	v_pk_add_f32 v[20:21], v[20:21], v[22:23]
	v_fma_f32 v34, -v32, v33, 1.0
	v_fmac_f32_e32 v33, v34, v33
	v_div_scale_f32 v34, vcc, v9, v25, v9
	v_mul_f32_e32 v35, v34, v33
	v_fma_f32 v36, -v32, v35, v34
	v_fmac_f32_e32 v35, v36, v33
	v_fma_f32 v32, -v32, v35, v34
	v_div_fmas_f32 v32, v32, v33, v35
	v_div_fixup_f32 v25, v32, v25, v9
	v_div_scale_f32 v9, s[12:13], v24, v24, v0
	v_rcp_f32_e32 v32, v9
	v_pk_add_f32 v[14:15], v[14:15], v[18:19]
	v_pk_mul_f32 v[22:23], v[20:21], v[20:21]
	v_pk_mul_f32 v[18:19], v[14:15], v[14:15]
	v_fma_f32 v33, -v9, v32, 1.0
	v_fmac_f32_e32 v32, v33, v32
	v_div_scale_f32 v33, vcc, v0, v24, v0
	v_mul_f32_e32 v34, v33, v32
	v_fma_f32 v35, -v9, v34, v33
	v_fmac_f32_e32 v34, v35, v32
	v_fma_f32 v9, -v9, v34, v33
	v_div_fmas_f32 v9, v9, v32, v34
	v_div_fixup_f32 v24, v9, v24, v0
	v_add_f32_e32 v0, v22, v23
	v_add_f32_e32 v0, v0, v18
	v_add_f32_e32 v0, v19, v0
	s_nop 1
	v_add_f32_dpp v0, v0, v0 quad_perm:[1,0,3,2] row_mask:0xf bank_mask:0xf
	s_nop 1
	v_add_f32_dpp v0, v0, v0 quad_perm:[2,3,0,1] row_mask:0xf bank_mask:0xf
	s_nop 1
	v_add_f32_dpp v0, v0, v0 row_half_mirror row_mask:0xf bank_mask:0xf
	s_nop 1
	v_add_f32_dpp v0, v0, v0 row_mirror row_mask:0xf bank_mask:0xf
	v_fmamk_f32 v0, v0, 0x3c800000, v229
	v_cmp_gt_f32_e32 vcc, s25, v0
	v_mul_f32_e32 v9, 0x4b800000, v0
	s_nop 0
	v_cndmask_b32_e32 v0, v0, v9, vcc
	v_rsq_f32_e32 v0, v0
	s_nop 0
	v_mul_f32_e32 v9, 0x45800000, v0
	v_cndmask_b32_e32 v0, v0, v9, vcc
	v_pk_mul_f32 v[14:15], v[14:15], v[0:1] op_sel_hi:[1,0]
	v_pk_mul_f32 v[18:19], v[20:21], v[0:1] op_sel_hi:[1,0]
	v_mov_b64_e32 v[10:11], v[116:117]
	v_mov_b64_e32 v[12:13], v[118:119]
	v_pk_mul_f32 v[12:13], v[12:13], v[14:15]
	v_pk_add_f32 v[14:15], v[26:27], 1.0 op_sel_hi:[1,0]
	v_mul_f32_e32 v9, 0xbfb8aa3b, v30
	v_div_scale_f32 v0, s[12:13], v15, v15, 1.0
	v_pk_mul_f32 v[10:11], v[10:11], v[18:19]
	v_exp_f32_e32 v18, v9
	v_rcp_f32_e32 v9, v0
	v_pk_mul_f32 v[10:11], v[28:29], v[10:11]
	v_fma_f32 v19, -v0, v9, 1.0
	v_fmac_f32_e32 v9, v19, v9
	v_div_scale_f32 v19, vcc, 1.0, v15, 1.0
	v_mul_f32_e32 v20, v19, v9
	v_fma_f32 v21, -v0, v20, v19
	v_fmac_f32_e32 v20, v21, v9
	v_fma_f32 v0, -v0, v20, v19
	v_div_fmas_f32 v0, v0, v9, v20
	v_div_fixup_f32 v15, v0, v15, 1.0
	v_div_scale_f32 v0, s[12:13], v14, v14, 1.0
	v_rcp_f32_e32 v9, v0
	v_pk_mul_f32 v[10:11], v[24:25], v[10:11]
	v_fma_f32 v19, -v0, v9, 1.0
	v_fmac_f32_e32 v9, v19, v9
	v_div_scale_f32 v19, vcc, 1.0, v14, 1.0
	v_mul_f32_e32 v20, v19, v9
	v_fma_f32 v21, -v0, v20, v19
	v_fmac_f32_e32 v20, v21, v9
	v_fma_f32 v0, -v0, v20, v19
	v_div_fmas_f32 v0, v0, v9, v20
	v_div_fixup_f32 v14, v0, v14, 1.0
	v_mul_f32_e32 v0, 0xbfb8aa3b, v31
	v_exp_f32_e32 v19, v0
	v_pk_mul_f32 v[12:13], v[14:15], v[12:13]
	v_cvt_pk_bf16_f32 v10, v10, v11
	v_pk_add_f32 v[14:15], v[18:19], 1.0 op_sel_hi:[1,0]
	s_nop 0
	v_div_scale_f32 v0, s[12:13], v15, v15, v31
	v_rcp_f32_e32 v9, v0
	s_nop 0
	v_fma_f32 v18, -v0, v9, 1.0
	v_fmac_f32_e32 v9, v18, v9
	v_div_scale_f32 v18, vcc, v31, v15, v31
	v_mul_f32_e32 v19, v18, v9
	v_fma_f32 v20, -v0, v19, v18
	v_fmac_f32_e32 v19, v20, v9
	v_fma_f32 v0, -v0, v19, v18
	v_div_fmas_f32 v0, v0, v9, v19
	v_div_fixup_f32 v15, v0, v15, v31
	v_div_scale_f32 v0, s[12:13], v14, v14, v30
	v_rcp_f32_e32 v9, v0
	s_nop 0
	v_fma_f32 v18, -v0, v9, 1.0
	v_fmac_f32_e32 v9, v18, v9
	v_div_scale_f32 v18, vcc, v30, v14, v30
	v_mul_f32_e32 v19, v18, v9
	v_fma_f32 v20, -v0, v19, v18
	v_fmac_f32_e32 v19, v20, v9
	v_fma_f32 v0, -v0, v19, v18
	v_div_fmas_f32 v0, v0, v9, v19
	v_div_fixup_f32 v14, v0, v14, v30
	v_pk_mul_f32 v[12:13], v[14:15], v[12:13]
	s_nop 0
	v_cvt_pk_bf16_f32 v11, v12, v13
	s_mov_b64 s[12:13], exec
	v_cmp_gt_u32_e32 vcc, s0, v121
	s_and_b64 exec, s[12:13], vcc
	global_store_dwordx2 v120, v[10:11], s[30:31] offset:1792
	s_mov_b64 exec, s[12:13]
	s_mul_i32 s8, s6, 8
	v_add_u32_e32 v121, s8, v2
	v_min_u32_e32 v20, s11, v121
	v_mul_hi_u32 v21, v20, s26
	v_lshrrev_b32_e32 v21, 6, v21
	v_mul_u32_u24_e32 v22, 0x60, v21
	v_sub_u32_e32 v22, v20, v22
	v_lshlrev_b32_e32 v23, 3, v22
	v_mul_u32_u24_e32 v24, 0x300, v21
	v_add_u32_e32 v24, v24, v23
	v_mul_lo_u32 v25, v21, s67
	v_add3_u32 v25, v25, v23, s61
	v_lshlrev_b32_e32 v26, 4, v22
	v_lshlrev_b32_e32 v27, 11, v21
	v_add_u32_e32 v27, 0x2a6f000, v27
	v_add_u32_e32 v120, v27, v23
	global_load_dwordx2 v[108:109], v24, s[14:15]
	global_load_dwordx2 v[110:111], v24, s[16:17]
	global_load_dwordx2 v[112:113], v25, s[36:37] offset:1024
	global_load_dwordx2 v[114:115], v25, s[36:37] offset:1792
	global_load_dwordx4 v[116:119], v26, s[4:5]
	v_cmp_gt_u32_e32 vcc, s0, v137
	s_cbranch_vccz .Lfin_done
; DI float bflo(unsigned v) { return __uint_as_float(v << 16); }
; DI float bfhi(unsigned v) { return __uint_as_float(v & 0xffff0000u); }
; DI float silu_f(float v) { return v / (1.f + __expf(-v)); }
; DI float sigmoid_f(float v) { return 1.f / (1.f + __expf(-v)); }
; DI void st_bf4(u16* dst, float a, float b, float c, float d) { uint2 u = {pk2(a, b), pk2(c, d)}; *(uint2*)dst = u; }
; DI void phase_fin(const Params& p, int layer, const VBC& vc) {
;     ...
;     for (long idx = (long)VBID * 256 + tid; idx < (long)ntok * 96; idx += (long)VGRID * 256) {
;         const int tok = (int)(idx / 96), rem = (int)(idx % 96), hd = rem >> 4, q = rem & 15, col = hd * 64 + q * 4;
;         uint2 a = *(const uint2*)(HF + (size_t)tok * 384 + col), bq = *(const uint2*)(HB + (size_t)tok * 384 + col);
;         float s0 = bflo(a.x) + bflo(bq.x), s1 = bfhi(a.x) + bfhi(bq.x), s2 = bflo(a.y) + bflo(bq.y), s3 = bfhi(a.y) + bfhi(bq.y);
;         float ss = s0 * s0 + s1 * s1 + s2 * s2 + s3 * s3;
;         ss += __shfl_xor(ss, 1); ss += __shfl_xor(ss, 2); ss += __shfl_xor(ss, 4); ss += __shfl_xor(ss, 8);
;         const float rs = rsqrtf(ss * (1.f / 64.f) + LN_EPS);
;         float4 gv = *(const float4*)(gn + col);
;         uint2 o = *(const uint2*)(P + (size_t)tok * PC + P_OM + col), z = *(const uint2*)(P + (size_t)tok * PC + P_ZM + col);
;         st_bf4(Y + (size_t)tok * LDK + 640 + col,
;                s0 * rs * gv.x * sigmoid_f(bflo(o.x)) * silu_f(bflo(z.x)), s1 * rs * gv.y * sigmoid_f(bfhi(o.x)) * silu_f(bfhi(z.x)),
;                s2 * rs * gv.z * sigmoid_f(bflo(o.y)) * silu_f(bflo(z.y)), s3 * rs * gv.w * sigmoid_f(bfhi(o.y)) * silu_f(bfhi(z.y)));
;     }
	s_waitcnt vmcnt(20)
	v_mov_b64_e32 v[14:15], v[124:125]
	v_mov_b64_e32 v[18:19], v[126:127]
	v_mov_b64_e32 v[26:27], v[128:129]
	v_mov_b64_e32 v[24:25], v[130:131]
	v_lshlrev_b32_e32 v20, 16, v14
	v_and_b32_e32 v21, 0xffff0000, v14
	v_lshlrev_b32_e32 v0, 16, v26
	v_and_b32_e32 v9, 0xffff0000, v26
	v_mul_f32_e32 v0, 0xbfb8aa3b, v0
	v_mul_f32_e32 v9, 0xbfb8aa3b, v9
	v_exp_f32_e32 v28, v0
	v_exp_f32_e32 v29, v9
	v_lshlrev_b32_e32 v30, 16, v25
	v_and_b32_e32 v31, 0xffff0000, v25
	v_lshlrev_b32_e32 v10, 16, v27
	v_pk_add_f32 v[28:29], v[28:29], 1.0 op_sel_hi:[1,0]
	v_mul_f32_e32 v10, 0xbfb8aa3b, v10
	v_div_scale_f32 v25, s[12:13], v29, v29, 1.0
	v_rcp_f32_e32 v32, v25
	v_exp_f32_e32 v26, v10
	v_and_b32_e32 v10, 0xffff0000, v27
	v_mul_f32_e32 v10, 0xbfb8aa3b, v10
	v_fma_f32 v33, -v25, v32, 1.0
	v_fmac_f32_e32 v32, v33, v32
	v_div_scale_f32 v33, vcc, 1.0, v29, 1.0
	v_mul_f32_e32 v34, v33, v32
	v_fma_f32 v35, -v25, v34, v33
	v_fmac_f32_e32 v34, v35, v32
	v_fma_f32 v25, -v25, v34, v33
	v_exp_f32_e32 v27, v10
	v_div_fmas_f32 v25, v25, v32, v34
	v_div_fixup_f32 v29, v25, v29, 1.0
	v_div_scale_f32 v25, s[12:13], v28, v28, 1.0
	v_rcp_f32_e32 v32, v25
	v_lshlrev_b32_e32 v0, 16, v24
	v_and_b32_e32 v9, 0xffff0000, v24
	v_mul_f32_e32 v24, 0xbfb8aa3b, v0
	v_fma_f32 v33, -v25, v32, 1.0
	v_fmac_f32_e32 v32, v33, v32
	v_div_scale_f32 v33, vcc, 1.0, v28, 1.0
	v_mul_f32_e32 v34, v33, v32
	v_fma_f32 v35, -v25, v34, v33
	v_fmac_f32_e32 v34, v35, v32
	v_fma_f32 v25, -v25, v34, v33
	v_div_fmas_f32 v25, v25, v32, v34
	v_div_fixup_f32 v28, v25, v28, 1.0
	v_mul_f32_e32 v25, 0xbfb8aa3b, v9
	v_exp_f32_e32 v24, v24
	v_exp_f32_e32 v25, v25
	v_lshlrev_b32_e32 v22, 16, v18
	v_and_b32_e32 v23, 0xffff0000, v18
	v_lshlrev_b32_e32 v14, 16, v15
	v_pk_add_f32 v[24:25], v[24:25], 1.0 op_sel_hi:[1,0]
	v_lshlrev_b32_e32 v18, 16, v19
	v_div_scale_f32 v32, s[12:13], v25, v25, v9
	v_rcp_f32_e32 v33, v32
	v_and_b32_e32 v15, 0xffff0000, v15
	v_and_b32_e32 v19, 0xffff0000, v19
	v_pk_add_f32 v[20:21], v[20:21], v[22:23]
	v_fma_f32 v34, -v32, v33, 1.0
	v_fmac_f32_e32 v33, v34, v33
	v_div_scale_f32 v34, vcc, v9, v25, v9
	v_mul_f32_e32 v35, v34, v33
	v_fma_f32 v36, -v32, v35, v34
	v_fmac_f32_e32 v35, v36, v33
	v_fma_f32 v32, -v32, v35, v34
	v_div_fmas_f32 v32, v32, v33, v35
	v_div_fixup_f32 v25, v32, v25, v9
	v_div_scale_f32 v9, s[12:13], v24, v24, v0
	v_rcp_f32_e32 v32, v9
	v_pk_add_f32 v[14:15], v[14:15], v[18:19]
	v_pk_mul_f32 v[22:23], v[20:21], v[20:21]
	v_pk_mul_f32 v[18:19], v[14:15], v[14:15]
	v_fma_f32 v33, -v9, v32, 1.0
	v_fmac_f32_e32 v32, v33, v32
	v_div_scale_f32 v33, vcc, v0, v24, v0
	v_mul_f32_e32 v34, v33, v32
	v_fma_f32 v35, -v9, v34, v33
	v_fmac_f32_e32 v34, v35, v32
	v_fma_f32 v9, -v9, v34, v33
	v_div_fmas_f32 v9, v9, v32, v34
	v_div_fixup_f32 v24, v9, v24, v0
	v_add_f32_e32 v0, v22, v23
	v_add_f32_e32 v0, v0, v18
	v_add_f32_e32 v0, v19, v0
	s_nop 1
	v_add_f32_dpp v0, v0, v0 quad_perm:[1,0,3,2] row_mask:0xf bank_mask:0xf
	s_nop 1
	v_add_f32_dpp v0, v0, v0 quad_perm:[2,3,0,1] row_mask:0xf bank_mask:0xf
	s_nop 1
	v_add_f32_dpp v0, v0, v0 row_half_mirror row_mask:0xf bank_mask:0xf
	s_nop 1
	v_add_f32_dpp v0, v0, v0 row_mirror row_mask:0xf bank_mask:0xf
	v_fmamk_f32 v0, v0, 0x3c800000, v229
	v_cmp_gt_f32_e32 vcc, s25, v0
	v_mul_f32_e32 v9, 0x4b800000, v0
	s_nop 0
	v_cndmask_b32_e32 v0, v0, v9, vcc
	v_rsq_f32_e32 v0, v0
	s_nop 0
	v_mul_f32_e32 v9, 0x45800000, v0
	v_cndmask_b32_e32 v0, v0, v9, vcc
	v_pk_mul_f32 v[14:15], v[14:15], v[0:1] op_sel_hi:[1,0]
	v_pk_mul_f32 v[18:19], v[20:21], v[0:1] op_sel_hi:[1,0]
	v_mov_b64_e32 v[10:11], v[132:133]
	v_mov_b64_e32 v[12:13], v[134:135]
	v_pk_mul_f32 v[12:13], v[12:13], v[14:15]
	v_pk_add_f32 v[14:15], v[26:27], 1.0 op_sel_hi:[1,0]
	v_mul_f32_e32 v9, 0xbfb8aa3b, v30
	v_div_scale_f32 v0, s[12:13], v15, v15, 1.0
	v_pk_mul_f32 v[10:11], v[10:11], v[18:19]
	v_exp_f32_e32 v18, v9
	v_rcp_f32_e32 v9, v0
	v_pk_mul_f32 v[10:11], v[28:29], v[10:11]
	v_fma_f32 v19, -v0, v9, 1.0
	v_fmac_f32_e32 v9, v19, v9
	v_div_scale_f32 v19, vcc, 1.0, v15, 1.0
	v_mul_f32_e32 v20, v19, v9
	v_fma_f32 v21, -v0, v20, v19
	v_fmac_f32_e32 v20, v21, v9
	v_fma_f32 v0, -v0, v20, v19
	v_div_fmas_f32 v0, v0, v9, v20
	v_div_fixup_f32 v15, v0, v15, 1.0
	v_div_scale_f32 v0, s[12:13], v14, v14, 1.0
	v_rcp_f32_e32 v9, v0
	v_pk_mul_f32 v[10:11], v[24:25], v[10:11]
	v_fma_f32 v19, -v0, v9, 1.0
	v_fmac_f32_e32 v9, v19, v9
	v_div_scale_f32 v19, vcc, 1.0, v14, 1.0
	v_mul_f32_e32 v20, v19, v9
	v_fma_f32 v21, -v0, v20, v19
	v_fmac_f32_e32 v20, v21, v9
	v_fma_f32 v0, -v0, v20, v19
	v_div_fmas_f32 v0, v0, v9, v20
	v_div_fixup_f32 v14, v0, v14, 1.0
	v_mul_f32_e32 v0, 0xbfb8aa3b, v31
	v_exp_f32_e32 v19, v0
	v_pk_mul_f32 v[12:13], v[14:15], v[12:13]
	v_cvt_pk_bf16_f32 v10, v10, v11
	v_pk_add_f32 v[14:15], v[18:19], 1.0 op_sel_hi:[1,0]
	s_nop 0
	v_div_scale_f32 v0, s[12:13], v15, v15, v31
	v_rcp_f32_e32 v9, v0
	s_nop 0
	v_fma_f32 v18, -v0, v9, 1.0
	v_fmac_f32_e32 v9, v18, v9
	v_div_scale_f32 v18, vcc, v31, v15, v31
	v_mul_f32_e32 v19, v18, v9
	v_fma_f32 v20, -v0, v19, v18
	v_fmac_f32_e32 v19, v20, v9
	v_fma_f32 v0, -v0, v19, v18
	v_div_fmas_f32 v0, v0, v9, v19
	v_div_fixup_f32 v15, v0, v15, v31
	v_div_scale_f32 v0, s[12:13], v14, v14, v30
	v_rcp_f32_e32 v9, v0
	s_nop 0
	v_fma_f32 v18, -v0, v9, 1.0
	v_fmac_f32_e32 v9, v18, v9
	v_div_scale_f32 v18, vcc, v30, v14, v30
	v_mul_f32_e32 v19, v18, v9
	v_fma_f32 v20, -v0, v19, v18
	v_fmac_f32_e32 v19, v20, v9
	v_fma_f32 v0, -v0, v19, v18
	v_div_fmas_f32 v0, v0, v9, v19
	v_div_fixup_f32 v14, v0, v14, v30
	v_pk_mul_f32 v[12:13], v[14:15], v[12:13]
	s_nop 0
	v_cvt_pk_bf16_f32 v11, v12, v13
	s_mov_b64 s[12:13], exec
	v_cmp_gt_u32_e32 vcc, s0, v137
	s_and_b64 exec, s[12:13], vcc
	global_store_dwordx2 v136, v[10:11], s[30:31] offset:1792
	s_mov_b64 exec, s[12:13]
	s_mul_i32 s8, s6, 9
	v_add_u32_e32 v137, s8, v2
	v_min_u32_e32 v20, s11, v137
	v_mul_hi_u32 v21, v20, s26
	v_lshrrev_b32_e32 v21, 6, v21
	v_mul_u32_u24_e32 v22, 0x60, v21
	v_sub_u32_e32 v22, v20, v22
	v_lshlrev_b32_e32 v23, 3, v22
	v_mul_u32_u24_e32 v24, 0x300, v21
	v_add_u32_e32 v24, v24, v23
	v_mul_lo_u32 v25, v21, s67
	v_add3_u32 v25, v25, v23, s61
	v_lshlrev_b32_e32 v26, 4, v22
	v_lshlrev_b32_e32 v27, 11, v21
	v_add_u32_e32 v27, 0x2a6f000, v27
	v_add_u32_e32 v136, v27, v23
	global_load_dwordx2 v[124:125], v24, s[14:15]
	global_load_dwordx2 v[126:127], v24, s[16:17]
	global_load_dwordx2 v[128:129], v25, s[36:37] offset:1024
	global_load_dwordx2 v[130:131], v25, s[36:37] offset:1792
	global_load_dwordx4 v[132:135], v26, s[4:5]
	v_add_u32_e32 v2, s9, v2
	s_branch .Lfin_top
; DI int lane_id() { int l; asm volatile("v_mbcnt_lo_u32_b32 %0, -1, 0\n\tv_mbcnt_hi_u32_b32 %0, -1, %0" : "=v"(l)); return l; }
; DI unsigned xb_add(unsigned* q, unsigned v) { return __hip_atomic_fetch_add(q, v, __ATOMIC_RELAXED, __HIP_MEMORY_SCOPE_AGENT); }
; DI void xcd_barrier(const XcdBarrier& b, int wid) {
;     asm volatile("s_waitcnt vmcnt(0)" ::: "memory");
;     __syncthreads();
;     if (wid == 0 && lane_id() == 0) {
;         unsigned* bar = b.bar;
;         __builtin_amdgcn_s_waitcnt(0);
;         unsigned nloc = b.st[0], nx = b.st[1];
;         if (nloc == 0u) { xcd_barrier_complete(bar, b.x, nloc, nx); b.st[0] = nloc; b.st[1] = nx; }
;         const unsigned old = xb_add(&bar[XB_XSUB(b.x)], 1u);
;         const unsigned gen = old / nloc;
;         if (old + 1u == (gen + 1u) * nloc) {
.Lfin_done:
	s_waitcnt vmcnt(0)
.LBB0_1124:
	s_mov_b32 s95, 0x800000
	s_or_b64 exec, exec, s[2:3]
	v_readlane_b32 s0, v251, 62
	s_add_i32 s16, s0, 5
	v_readlane_b32 s0, v252, 19
	v_readlane_b32 s1, v252, 20
	s_cmp_ge_i32 s16, s1
	s_cbranch_scc1 .LBB0_1180
	s_waitcnt vmcnt(0)
	v_readlane_b32 s0, v252, 1
	v_readlane_b32 s1, v252, 2
	s_and_b64 vcc, exec, s[0:1]
	s_waitcnt vmcnt(0)
	s_barrier
	s_cbranch_vccnz .LBB0_1179
	v_mbcnt_lo_u32_b32 v0, -1, 0
	v_mbcnt_hi_u32_b32 v0, -1, v0
	s_nop 0
	v_cmp_eq_u32_e32 vcc, 0, v0
	s_and_saveexec_b64 s[0:1], vcc
	s_cbranch_execz .LBB0_1178
	v_readlane_b32 s2, v251, 56
	s_waitcnt vmcnt(0) expcnt(0) lgkmcnt(0)
	s_nop 0
	v_mov_b32_e32 v0, s2
	ds_read_b32 v3, v0
	v_readlane_b32 s2, v251, 57
	s_waitcnt lgkmcnt(0)
	v_cmp_ne_u32_e32 vcc, 0, v3
	v_mov_b32_e32 v0, s2
	ds_read_b32 v2, v0
	s_cbranch_vccnz .LBB0_1142
	s_mov_b32 s8, 1
	s_branch .LBB0_1130
